# seam leader bumps the per-XCD generation before its own cache invalidate (waiting workgroups released one invalidate earlier)
# baseline (speedup 1.0000x reference)
.LBB0_400:
	s_mov_b64 s[10:11], exec
	v_mbcnt_lo_u32_b32 v0, s10, 0
	v_mbcnt_hi_u32_b32 v0, s11, v0
	v_cmp_eq_u32_e32 vcc, 0, v0
	s_waitcnt vmcnt(0) lgkmcnt(0)
	s_and_saveexec_b64 s[14:15], vcc
	s_cbranch_execz .LBB0_402
	s_bcnt1_i32_b64 s10, s[10:11]
	v_mov_b32_e32 v0, s10
	global_atomic_add v223, v0, s[12:13] offset:1024
.LBB0_402:
	s_or_b64 exec, exec, s[14:15]
	buffer_inv sc1
	s_waitcnt vmcnt(0)

.LBB0_502:
	s_or_b64 exec, exec, s[10:11]
	s_mov_b64 s[10:11], exec
	v_mbcnt_lo_u32_b32 v0, s10, 0
	v_mbcnt_hi_u32_b32 v0, s11, v0
	v_cmp_eq_u32_e32 vcc, 0, v0
	s_waitcnt vmcnt(0) lgkmcnt(0)
	s_and_saveexec_b64 s[14:15], vcc
	s_cbranch_execz .LBB0_504
	s_bcnt1_i32_b64 s10, s[10:11]
	v_mov_b32_e32 v0, s10
	global_atomic_add v223, v0, s[12:13] offset:1024

.LBB0_2123:
	s_or_b64 exec, exec, s[8:9]
	s_mov_b64 s[8:9], exec
	v_mbcnt_lo_u32_b32 v0, s8, 0
	v_mbcnt_hi_u32_b32 v0, s9, v0
	v_cmp_eq_u32_e32 vcc, 0, v0
	s_waitcnt vmcnt(0) lgkmcnt(0)
	s_and_saveexec_b64 s[14:15], vcc
	s_cbranch_execz .LBB0_2125
	s_bcnt1_i32_b64 s1, s[8:9]
	v_mov_b32_e32 v0, s1
	global_atomic_add v223, v0, s[10:11] offset:1024
